# P4 scan loop: counted vmcnt waits per wave class so the chunk prefetch stays in flight across the half-iteration barrier (on top of nop removal)
# baseline (speedup 1.0000x reference)
.LBB0_677:
	s_or_b64 exec, exec, s[20:21]
	s_andn2_b64 vcc, exec, s[18:19]
	s_cbranch_vccnz .Lp4_h1_drain
	s_and_b64 vcc, exec, s[4:5]
	s_cbranch_vccnz .Lp4_h1_c
	s_and_b64 vcc, exec, s[6:7]
	s_cbranch_vccnz .Lp4_h1_m
	s_waitcnt vmcnt(7)
	s_branch .Lp4_h1_go
.Lp4_h1_m:
	s_waitcnt vmcnt(8)
	s_branch .Lp4_h1_go
.Lp4_h1_c:
	s_waitcnt vmcnt(24)
	s_branch .Lp4_h1_go

.Lp4_h1_go:
	ds_write_b128 v154, v[38:41]
	ds_write_b128 v154, v[42:45] offset:8192
	ds_write_b128 v154, v[46:49] offset:16384
	ds_write_b128 v154, v[50:53] offset:24576
	ds_write_b128 v154, v[54:57] offset:32768
	ds_write_b128 v154, v[58:61] offset:40960
	ds_write_b128 v154, v[62:65] offset:49152
	s_and_saveexec_b64 s[20:21], s[6:7]
	v_add_u32_e32 v98, 0, v126
	v_add_u32_e32 v98, 0x1d000, v98
	ds_write_b128 v98, v[6:9]
	s_or_b64 exec, exec, s[20:21]
	s_cmp_gt_u32 s15, 60
	s_waitcnt lgkmcnt(0)
	s_barrier
	s_cbranch_scc0 .LBB0_682
	s_and_saveexec_b64 s[20:21], s[4:5]
	s_cbranch_execnz .LBB0_685

.LBB0_686:
	s_and_b64 vcc, exec, s[4:5]
	s_cbranch_vccnz .Lp4_h2_c
	s_and_b64 vcc, exec, s[6:7]
	s_cbranch_vccnz .Lp4_h2_m
	s_waitcnt vmcnt(7)
	s_branch .Lp4_h2_go

.Lp4_h2_c:
	s_waitcnt vmcnt(40)
